# SSD scan: C tile stored with an XOR-8 swizzle (rows with bit 3 swap 8-byte halves) so the 16-row fragment reads are bank-conflict free
# speedup vs baseline: 1.0016x; 1.0016x over previous
.LBB0_64:
	s_add_u32 s37, s54, 0x1cbc0000
	s_addc_u32 s38, s55, 0
	s_add_u32 s20, s54, 0x16f80000
	s_addc_u32 s21, s55, 0
	s_and_b64 s[4:5], s[68:69], exec
	s_movk_i32 s4, 0x280
	s_cselect_b32 s39, s4, 0x80
	s_add_i32 s40, s2, 0x80
	s_and_b64 s[4:5], s[68:69], exec
	v_lshlrev_b32_e32 v4, 3, v218
	v_readlane_b32 s4, v255, 8
	v_and_b32_e32 v71, 0x78, v4
	s_cselect_b32 s41, 8, 0
	v_or_b32_e32 v70, s4, v219
	v_lshlrev_b32_e32 v0, 1, v71
	v_ashrrev_i32_e32 v161, 31, v160
	s_lshl_b32 s4, s4, 1
	v_lshl_add_u64 v[2:3], s[54:55], 0, v[0:1]
	s_mov_b64 s[6:7], 0x1ddc0000
	v_lshlrev_b64 v[76:77], 4, v[160:161]
	v_lshlrev_b32_e32 v6, 2, v158
	v_readlane_b32 s5, v255, 13
	s_add_u32 s4, s54, s4
	v_lshl_add_u64 v[74:75], v[2:3], 0, s[6:7]
	v_lshl_add_u64 v[2:3], s[54:55], 0, v[76:77]
	s_mov_b64 s[6:7], 0x171c0000
	v_add_u32_e32 v104, s5, v6
	s_addc_u32 s5, s55, 0
	v_lshlrev_b32_e32 v80, 3, v38
	v_mov_b32_e32 v81, v1
	v_lshl_add_u64 v[78:79], v[2:3], 0, s[6:7]
	v_add_u32_e32 v73, 0, v0
	v_lshl_add_u64 v[2:3], s[4:5], 0, v[80:81]
	s_mov_b64 s[4:5], 0x10380000
	v_lshlrev_b32_e32 v0, 9, v70
	v_lshl_add_u64 v[82:83], v[2:3], 0, s[4:5]
	v_lshl_add_u64 v[2:3], s[52:53], 0, v[0:1]
	v_lshlrev_b32_e32 v0, 4, v38
	v_and_b32_e32 v102, 56, v4
	v_lshl_add_u64 v[84:85], v[2:3], 0, v[0:1]
	v_add_u32_e32 v2, 0x200, v160
	v_lshlrev_b32_e32 v4, 1, v102
	v_ashrrev_i32_e32 v3, 31, v2
	v_readlane_b32 s16, v255, 30
	v_ashrrev_i32_e32 v88, 4, v2
	v_lshlrev_b64 v[90:91], 4, v[2:3]
	s_movk_i32 s4, 0x90
	v_lshrrev_b32_e32 v2, 3, v2
	v_add_u32_e32 v110, s16, v4
	v_readlane_b32 s16, v255, 31
	v_mul_lo_u32 v109, v2, s4
	s_movk_i32 s17, 0x110
	v_add_u32_e32 v2, s16, v4
	v_readlane_b32 s16, v255, 21
	v_mov_b32_e32 v3, 0x1100
	v_lshrrev_b32_e32 v5, 3, v160
	v_add_u32_e32 v111, s16, v6
	v_readlane_b32 s16, v255, 22
	v_mul_u32_u24_e32 v105, 0x90, v70
	v_mul_u32_u24_e32 v112, 0x110, v219
	v_mad_u32_u24 v114, v219, s17, v3
	v_mov_b32_e32 v3, 0x2200
	v_lshl_add_u32 v120, v219, 2, s16
	v_lshl_add_u32 v121, v38, 5, s16
	v_readlane_b32 s16, v255, 23
	v_ashrrev_i32_e32 v86, 4, v160
	v_mul_lo_u32 v107, v5, s4
	v_add3_u32 v113, 0, v112, v80
	v_and_b32_e32 v189, 8, v219
	v_xor_b32_e32 v113, v113, v189
	v_mad_u32_u24 v116, v219, s17, v3
	v_mov_b32_e32 v3, 0x3300
	v_add3_u32 v122, s16, v105, v0
	v_add_u32_e32 v0, 0, v0
	v_mul_u32_u24_e32 v123, 0x90, v219
	v_lshlrev_b32_e32 v72, 2, v38
	v_add_u32_e32 v103, 0, v4
	v_or_b32_e32 v81, 0xffffffc0, v219
	v_ashrrev_i32_e32 v87, 31, v86
	v_ashrrev_i32_e32 v89, 31, v88
	v_mul_lo_u32 v106, v86, s17
	v_mul_lo_u32 v108, v88, s17
	v_cmp_eq_u32_e64 s[4:5], 0, v158
	v_cmp_gt_u32_e64 s[6:7], 2, v158
	v_cmp_gt_u32_e64 s[8:9], 4, v158
	v_cmp_gt_u32_e64 s[10:11], 8, v158
	v_cmp_gt_u32_e64 s[12:13], 16, v158
	v_cmp_gt_u32_e64 s[14:15], 32, v158
	v_add_u32_e32 v115, 0x1100, v113
	v_add_u32_e32 v117, 0x2200, v113
	v_mad_u32_u24 v118, v219, s17, v3
	v_add_u32_e32 v119, 0x3300, v113
	s_sub_i32 s42, 0xc0, s92
	v_add_u32_e32 v124, v2, v107
	v_add_u32_e32 v125, v0, v123
	v_readlane_b32 s84, v255, 34
	v_readlane_b32 s91, v255, 35
	v_readlane_b32 s50, v255, 4
	s_mov_b32 s63, 0x8000
	s_branch .LBB0_68

.LBB0_95:
	s_waitcnt vmcnt(6)
	v_mul_f32_e32 v0, 0x3fb8aa3b, v58
	v_exp_f32_e32 v0, v0
	v_add_u32_e32 v58, v73, v106
	s_waitcnt vmcnt(5)
	s_bitcmp1_b32 s91, 1
	s_cbranch_scc1 .Lswz_w8
	ds_write_b128 v58, v[6:9]
	s_branch .Lswz_e8
.Lswz_w8:
	ds_write_b64 v58, v[8:9]
	ds_write_b64 v58, v[6:7] offset:8
.Lswz_e8:
	v_add_u32_e32 v6, v103, v107
	s_waitcnt vmcnt(4)
	ds_write_b128 v6, v[2:5] offset:17408
	s_waitcnt vmcnt(3)
	ds_write_b128 v6, v[14:17] offset:35840
	v_add_u32_e32 v59, v73, v108
	v_add_u32_e32 v2, v103, v109
	s_and_b64 vcc, exec, s[16:17]
	s_waitcnt vmcnt(2)
	s_bitcmp1_b32 s91, 1
	s_cbranch_scc1 .Lswz_w7
	ds_write_b128 v59, v[10:13]
	s_branch .Lswz_e7
.Lswz_w7:
	ds_write_b64 v59, v[12:13]
	ds_write_b64 v59, v[10:11] offset:8
.Lswz_e7:
	s_waitcnt vmcnt(1)
	ds_write_b128 v2, v[18:21] offset:17408
	s_waitcnt vmcnt(0)
	ds_write_b128 v6, v[22:25] offset:45056
	s_cbranch_vccnz .LBB0_97
	v_cmp_lt_i32_e32 vcc, v194, v193
	v_mul_f32_e64 v2, v126, -v0
	s_nop 0
	v_cndmask_b32_e32 v3, v194, v192, vcc
	v_lshlrev_b32_e32 v3, 2, v3
	ds_bpermute_b32 v3, v3, v2
	v_cmp_lt_i32_e32 vcc, v195, v193
	s_waitcnt lgkmcnt(0)
	v_fma_f32 v3, v126, -v0, v3
	v_cndmask_b32_e64 v2, v3, v2, s[4:5]
	v_cndmask_b32_e32 v3, v195, v192, vcc
	v_lshlrev_b32_e32 v3, 2, v3
	ds_bpermute_b32 v3, v3, v2
	v_cmp_lt_i32_e32 vcc, v196, v193
	s_waitcnt lgkmcnt(0)
	v_add_f32_e32 v3, v2, v3
	v_cndmask_b32_e64 v2, v3, v2, s[6:7]
	v_cndmask_b32_e32 v3, v196, v192, vcc
	v_lshlrev_b32_e32 v3, 2, v3
	ds_bpermute_b32 v3, v3, v2
	v_cmp_lt_i32_e32 vcc, v197, v193
	s_waitcnt lgkmcnt(0)
	v_add_f32_e32 v3, v2, v3
	v_cndmask_b32_e64 v2, v3, v2, s[8:9]
	v_cndmask_b32_e32 v3, v197, v192, vcc
	v_lshlrev_b32_e32 v3, 2, v3
	ds_bpermute_b32 v3, v3, v2
	v_cmp_lt_i32_e32 vcc, v198, v193
	s_waitcnt lgkmcnt(0)
	v_add_f32_e32 v3, v2, v3
	v_cndmask_b32_e64 v2, v3, v2, s[10:11]
	v_cndmask_b32_e32 v3, v198, v192, vcc
	v_lshlrev_b32_e32 v3, 2, v3
	ds_bpermute_b32 v3, v3, v2
	v_cmp_lt_i32_e32 vcc, v199, v193
	s_waitcnt lgkmcnt(0)
	v_add_f32_e32 v3, v2, v3
	v_cndmask_b32_e64 v2, v3, v2, s[12:13]
	v_cndmask_b32_e32 v3, v199, v192, vcc
	v_lshlrev_b32_e32 v3, 2, v3
	ds_bpermute_b32 v3, v3, v2
	s_waitcnt lgkmcnt(0)
	v_add_f32_e32 v3, v2, v3
	v_cndmask_b32_e64 v2, v3, v2, s[14:15]
	v_lshl_or_b32 v3, v192, 2, v200
	ds_bpermute_b32 v3, v3, v2
	s_waitcnt lgkmcnt(0)
	v_sub_f32_e32 v3, v3, v2
	v_mul_f32_e32 v3, 0x3fb8aa3b, v3
	v_exp_f32_e32 v3, v3
	s_nop 0
	v_mul_f32_e32 v3, v126, v3
	ds_write2st64_b32 v104, v2, v3 offset0:212 offset1:214

.LBB0_99:
	s_add_u32 s27, s37, s23
	s_addc_u32 s29, s38, 0
	s_lshl_b32 s19, s88, 2
	s_add_u32 s19, s20, s19
	s_addc_u32 s23, s21, 0
	s_lshl_b32 s18, s18, 2
	s_add_u32 s18, s19, s18
	s_addc_u32 s19, s23, 0
	s_lshl_b32 s23, s91, 2
	s_add_u32 s30, s18, s23
	s_addc_u32 s31, s19, 0
	v_cmp_ne_u32_e64 s[18:19], 1, v60
	s_andn2_b64 vcc, exec, s[24:25]
	s_waitcnt lgkmcnt(0)
	s_barrier
	s_cbranch_vccnz .LBB0_104
	s_waitcnt vmcnt(5)
	s_bitcmp1_b32 s91, 1
	s_cbranch_scc1 .Lswz_w6
	ds_write_b128 v58, v[2:5] offset:55296
	s_branch .Lswz_e6
.Lswz_w6:
	ds_write_b64 v58, v[4:5] offset:55296
	ds_write_b64 v58, v[2:3] offset:55304
.Lswz_e6:
	v_add_u32_e32 v2, v110, v107
	s_waitcnt vmcnt(4)
	ds_write_b128 v2, v[6:9]
	s_waitcnt vmcnt(3)
	ds_write_b128 v124, v[10:13]
	s_waitcnt vmcnt(2)
	s_bitcmp1_b32 s91, 1
	s_cbranch_scc1 .Lswz_w5
	ds_write_b128 v59, v[14:17] offset:55296
	s_branch .Lswz_e5
.Lswz_w5:
	ds_write_b64 v59, v[16:17] offset:55296
	ds_write_b64 v59, v[14:15] offset:55304
.Lswz_e5:
	v_add_u32_e32 v2, v110, v109
	s_and_b64 vcc, exec, s[16:17]
	s_waitcnt vmcnt(1)
	ds_write_b128 v2, v[18:21]
	s_waitcnt vmcnt(0)
	ds_write_b128 v124, v[22:25] offset:9216
	s_cbranch_vccnz .LBB0_102
	v_cmp_lt_i32_e32 vcc, v194, v193
	v_mul_f32_e64 v2, v126, -v0
	s_nop 0
	v_cndmask_b32_e32 v3, v194, v192, vcc
	v_lshlrev_b32_e32 v3, 2, v3
	ds_bpermute_b32 v3, v3, v2
	v_cmp_lt_i32_e32 vcc, v195, v193
	s_waitcnt lgkmcnt(0)
	v_fma_f32 v3, v126, -v0, v3
	v_cndmask_b32_e64 v2, v3, v2, s[4:5]
	v_cndmask_b32_e32 v3, v195, v192, vcc
	v_lshlrev_b32_e32 v3, 2, v3
	ds_bpermute_b32 v3, v3, v2
	v_cmp_lt_i32_e32 vcc, v196, v193
	s_waitcnt lgkmcnt(0)
	v_add_f32_e32 v3, v2, v3
	v_cndmask_b32_e64 v2, v3, v2, s[6:7]
	v_cndmask_b32_e32 v3, v196, v192, vcc
	v_lshlrev_b32_e32 v3, 2, v3
	ds_bpermute_b32 v3, v3, v2
	v_cmp_lt_i32_e32 vcc, v197, v193
	s_waitcnt lgkmcnt(0)
	v_add_f32_e32 v3, v2, v3
	v_cndmask_b32_e64 v2, v3, v2, s[8:9]
	v_cndmask_b32_e32 v3, v197, v192, vcc
	v_lshlrev_b32_e32 v3, 2, v3
	ds_bpermute_b32 v3, v3, v2
	v_cmp_lt_i32_e32 vcc, v198, v193
	s_waitcnt lgkmcnt(0)
	v_add_f32_e32 v3, v2, v3
	v_cndmask_b32_e64 v2, v3, v2, s[10:11]
	v_cndmask_b32_e32 v3, v198, v192, vcc
	v_lshlrev_b32_e32 v3, 2, v3
	ds_bpermute_b32 v3, v3, v2
	v_cmp_lt_i32_e32 vcc, v199, v193
	s_waitcnt lgkmcnt(0)
	v_add_f32_e32 v3, v2, v3
	v_cndmask_b32_e64 v2, v3, v2, s[12:13]
	v_cndmask_b32_e32 v3, v199, v192, vcc
	v_lshlrev_b32_e32 v3, 2, v3
	ds_bpermute_b32 v3, v3, v2
	s_waitcnt lgkmcnt(0)
	v_add_f32_e32 v3, v2, v3
	v_cndmask_b32_e64 v2, v3, v2, s[14:15]
	v_lshl_or_b32 v3, v192, 2, v200
	ds_bpermute_b32 v3, v3, v2
	s_waitcnt lgkmcnt(0)
	v_sub_f32_e32 v3, v3, v2
	v_mul_f32_e32 v3, 0x3fb8aa3b, v3
	v_exp_f32_e32 v3, v3
	s_nop 0
	v_mul_f32_e32 v3, v126, v3
	ds_write2st64_b32 v111, v2, v3 offset1:2

.LBB0_106:
	s_bitcmp1_b32 s34, 0
	s_cbranch_scc1 .Lscan_B106
	s_bitcmp1_b32 s34, 0
	s_cselect_b32 s19, 0xd800, 0
	s_add_i32 s19, s19, 0
	v_lshl_add_u32 v58, v71, 1, s19
	v_lshl_add_u32 v59, v102, 1, s19
	v_add_u32_e32 v60, v58, v106
	s_waitcnt vmcnt(19)
	s_bitcmp1_b32 s91, 1
	s_cbranch_scc1 .Lswz_w4
	ds_write_b128 v60, v[2:5]
	s_branch .Lswz_e4
.Lswz_w4:
	ds_write_b64 v60, v[4:5]
	ds_write_b64 v60, v[2:3] offset:8
.Lswz_e4:
	v_add_u32_e32 v60, v59, v107
	v_add_u32_e32 v58, v58, v108
	s_waitcnt vmcnt(18)
	ds_write_b128 v60, v[6:9] offset:17408
	s_waitcnt vmcnt(17)
	ds_write_b128 v60, v[10:13] offset:35840
	s_waitcnt vmcnt(16)
	s_bitcmp1_b32 s91, 1
	s_cbranch_scc1 .Lswz_w3
	ds_write_b128 v58, v[14:17]
	s_branch .Lswz_e3
.Lswz_w3:
	ds_write_b64 v58, v[16:17]
	ds_write_b64 v58, v[14:15] offset:8
.Lswz_e3:
	v_add_u32_e32 v58, v59, v109
	s_and_b64 vcc, exec, s[16:17]
	s_waitcnt vmcnt(15)
	ds_write_b128 v58, v[18:21] offset:17408
	s_waitcnt vmcnt(14)
	ds_write_b128 v60, v[22:25] offset:45056
	s_cbranch_vccnz .LBB0_108
	v_cmp_lt_i32_e32 vcc, v194, v193
	v_mul_f32_e64 v58, v126, -v0
	s_add_i32 s19, s19, s50
	v_cndmask_b32_e32 v59, v194, v192, vcc
	v_lshlrev_b32_e32 v59, 2, v59
	ds_bpermute_b32 v59, v59, v58
	v_cmp_lt_i32_e32 vcc, v195, v193
	s_waitcnt lgkmcnt(0)
	v_fma_f32 v59, v126, -v0, v59
	v_cndmask_b32_e32 v60, v195, v192, vcc
	v_cndmask_b32_e64 v58, v59, v58, s[4:5]
	v_lshlrev_b32_e32 v59, 2, v60
	ds_bpermute_b32 v59, v59, v58
	v_cmp_lt_i32_e32 vcc, v196, v193
	s_waitcnt lgkmcnt(0)
	v_add_f32_e32 v59, v58, v59
	v_cndmask_b32_e32 v60, v196, v192, vcc
	v_lshlrev_b32_e32 v60, 2, v60
	v_cndmask_b32_e64 v58, v59, v58, s[6:7]
	ds_bpermute_b32 v59, v60, v58
	v_cmp_lt_i32_e32 vcc, v197, v193
	s_waitcnt lgkmcnt(0)
	v_add_f32_e32 v59, v58, v59
	v_cndmask_b32_e32 v60, v197, v192, vcc
	v_lshlrev_b32_e32 v60, 2, v60
	v_cndmask_b32_e64 v58, v59, v58, s[8:9]
	ds_bpermute_b32 v59, v60, v58
	v_cmp_lt_i32_e32 vcc, v198, v193
	s_waitcnt lgkmcnt(0)
	v_add_f32_e32 v59, v58, v59
	v_cndmask_b32_e32 v60, v198, v192, vcc
	v_lshlrev_b32_e32 v60, 2, v60
	v_cndmask_b32_e64 v58, v59, v58, s[10:11]
	ds_bpermute_b32 v59, v60, v58
	v_cmp_lt_i32_e32 vcc, v199, v193
	s_waitcnt lgkmcnt(0)
	v_add_f32_e32 v59, v58, v59
	v_cndmask_b32_e32 v60, v199, v192, vcc
	v_lshlrev_b32_e32 v60, 2, v60
	v_cndmask_b32_e64 v58, v59, v58, s[12:13]
	ds_bpermute_b32 v59, v60, v58
	v_lshl_add_u32 v60, v158, 2, s19
	s_waitcnt lgkmcnt(0)
	v_add_f32_e32 v59, v58, v59
	v_cndmask_b32_e64 v58, v59, v58, s[14:15]
	v_lshl_or_b32 v59, v192, 2, v200
	ds_bpermute_b32 v59, v59, v58
	s_waitcnt lgkmcnt(0)
	v_sub_f32_e32 v59, v59, v58
	v_mul_f32_e32 v59, 0x3fb8aa3b, v59
	v_exp_f32_e32 v59, v59
	s_nop 0
	v_mul_f32_e32 v59, v126, v59
	ds_write2st64_b32 v60, v58, v59 offset0:212 offset1:214

.Lscan_B106:
	s_bitcmp1_b32 s34, 0
	s_cselect_b32 s19, 0xd800, 0
	s_add_i32 s19, s19, 0
	v_lshl_add_u32 v58, v71, 1, s19
	v_lshl_add_u32 v59, v102, 1, s19
	v_add_u32_e32 v60, v58, v106
	s_waitcnt vmcnt(19)
	s_bitcmp1_b32 s91, 1
	s_cbranch_scc1 .Lswz_w2
	ds_write_b128 v60, v[220:223]
	s_branch .Lswz_e2
.Lswz_w2:
	ds_write_b64 v60, v[222:223]
	ds_write_b64 v60, v[220:221] offset:8
.Lswz_e2:
	v_add_u32_e32 v60, v59, v107
	v_add_u32_e32 v58, v58, v108
	s_waitcnt vmcnt(18)
	ds_write_b128 v60, v[224:227] offset:17408
	s_waitcnt vmcnt(17)
	ds_write_b128 v60, v[228:231] offset:35840
	s_waitcnt vmcnt(16)
	s_bitcmp1_b32 s91, 1
	s_cbranch_scc1 .Lswz_w1
	ds_write_b128 v58, v[232:235]
	s_branch .Lswz_e1
.Lswz_w1:
	ds_write_b64 v58, v[234:235]
	ds_write_b64 v58, v[232:233] offset:8
.Lswz_e1:
	v_add_u32_e32 v58, v59, v109
	s_and_b64 vcc, exec, s[16:17]
	s_waitcnt vmcnt(15)
	ds_write_b128 v58, v[236:239] offset:17408
	s_waitcnt vmcnt(14)
	ds_write_b128 v60, v[240:243] offset:45056
	s_cbranch_vccnz .Lscan_B108
	v_cmp_lt_i32_e32 vcc, v194, v193
	v_mul_f32_e64 v58, v244, -v0
	s_add_i32 s19, s19, s50
	v_cndmask_b32_e32 v59, v194, v192, vcc
	v_lshlrev_b32_e32 v59, 2, v59
	ds_bpermute_b32 v59, v59, v58
	v_cmp_lt_i32_e32 vcc, v195, v193
	s_waitcnt lgkmcnt(0)
	v_fma_f32 v59, v244, -v0, v59
	v_cndmask_b32_e32 v60, v195, v192, vcc
	v_cndmask_b32_e64 v58, v59, v58, s[4:5]
	v_lshlrev_b32_e32 v59, 2, v60
	ds_bpermute_b32 v59, v59, v58
	v_cmp_lt_i32_e32 vcc, v196, v193
	s_waitcnt lgkmcnt(0)
	v_add_f32_e32 v59, v58, v59
	v_cndmask_b32_e32 v60, v196, v192, vcc
	v_lshlrev_b32_e32 v60, 2, v60
	v_cndmask_b32_e64 v58, v59, v58, s[6:7]
	ds_bpermute_b32 v59, v60, v58
	v_cmp_lt_i32_e32 vcc, v197, v193
	s_waitcnt lgkmcnt(0)
	v_add_f32_e32 v59, v58, v59
	v_cndmask_b32_e32 v60, v197, v192, vcc
	v_lshlrev_b32_e32 v60, 2, v60
	v_cndmask_b32_e64 v58, v59, v58, s[8:9]
	ds_bpermute_b32 v59, v60, v58
	v_cmp_lt_i32_e32 vcc, v198, v193
	s_waitcnt lgkmcnt(0)
	v_add_f32_e32 v59, v58, v59
	v_cndmask_b32_e32 v60, v198, v192, vcc
	v_lshlrev_b32_e32 v60, 2, v60
	v_cndmask_b32_e64 v58, v59, v58, s[10:11]
	ds_bpermute_b32 v59, v60, v58
	v_cmp_lt_i32_e32 vcc, v199, v193
	s_waitcnt lgkmcnt(0)
	v_add_f32_e32 v59, v58, v59
	v_cndmask_b32_e32 v60, v199, v192, vcc
	v_lshlrev_b32_e32 v60, 2, v60
	v_cndmask_b32_e64 v58, v59, v58, s[12:13]
	ds_bpermute_b32 v59, v60, v58
	v_lshl_add_u32 v60, v158, 2, s19
	s_waitcnt lgkmcnt(0)
	v_add_f32_e32 v59, v58, v59
	v_cndmask_b32_e64 v58, v59, v58, s[14:15]
	v_lshl_or_b32 v59, v192, 2, v200
	ds_bpermute_b32 v59, v59, v58
	s_waitcnt lgkmcnt(0)
	v_sub_f32_e32 v59, v59, v58
	v_mul_f32_e32 v59, 0x3fb8aa3b, v59
	v_exp_f32_e32 v59, v59
	s_nop 0
	v_mul_f32_e32 v59, v244, v59
	ds_write2st64_b32 v60, v58, v59 offset0:212 offset1:214

.LBB0_111:
	s_bitcmp1_b32 s35, 0
	s_cselect_b32 s19, 0xd800, 0
	s_add_i32 s19, s19, 0
	v_lshlrev_b32_e32 v68, 1, v72
	v_xor_b32_e32 v68, v68, v189
	v_add3_u32 v127, s19, v112, v68
	ds_read2_b64 v[58:61], v127 offset1:4
	v_add3_u32 v148, s19, v114, v68
	ds_read2_b64 v[128:131], v148 offset1:4
	v_add3_u32 v149, s19, v116, v68
	v_add3_u32 v150, s19, v118, v68
	ds_read2_b64 v[132:135], v149 offset1:4
	ds_read2_b64 v[136:139], v150 offset1:4
	ds_read2_b64 v[140:143], v127 offset0:8 offset1:12
	v_cvt_pk_bf16_f32 v62, v50, v51
	v_cvt_pk_bf16_f32 v63, v52, v53
	v_cvt_pk_bf16_f32 v64, v26, v27
	v_cvt_pk_bf16_f32 v65, v28, v29
	v_add_u32_e32 v151, s18, v219
	s_waitcnt lgkmcnt(4)
	v_mfma_f32_16x16x32_bf16 v[58:61], v[62:65], v[58:61], 0
	ds_read2_b64 v[144:147], v148 offset0:8 offset1:12
	v_add_u32_e32 v68, 0xffffff40, v151
	v_ashrrev_i32_e32 v69, 31, v68
	s_waitcnt lgkmcnt(4)
	v_mfma_f32_16x16x32_bf16 v[128:131], v[62:65], v[128:131], 0
	v_lshlrev_b64 v[68:69], 12, v[68:69]
	v_lshl_add_u64 v[68:69], v[94:95], 0, v[68:69]
	global_store_dwordx2 v[68:69], v[100:101], off
	s_waitcnt lgkmcnt(3)
	v_mfma_f32_16x16x32_bf16 v[132:135], v[62:65], v[132:135], 0
	v_add_u32_e32 v68, 0xffffff50, v151
	v_ashrrev_i32_e32 v69, 31, v68
	v_lshlrev_b64 v[68:69], 12, v[68:69]
	s_waitcnt lgkmcnt(2)
	v_mfma_f32_16x16x32_bf16 v[62:65], v[62:65], v[136:139], 0
	v_cvt_pk_bf16_f32 v136, v30, v31
	v_cvt_pk_bf16_f32 v137, v32, v33
	v_cvt_pk_bf16_f32 v138, v34, v35
	v_cvt_pk_bf16_f32 v139, v36, v37
	v_lshl_add_u64 v[68:69], v[94:95], 0, v[68:69]
	s_waitcnt lgkmcnt(1)
	v_mfma_f32_16x16x32_bf16 v[58:61], v[136:139], v[140:143], v[58:61]
	ds_read2_b64 v[140:143], v149 offset0:8 offset1:12
	global_store_dwordx2 v[68:69], v[98:99], off
	ds_read2_b64 v[98:101], v149 offset0:16 offset1:20
	s_waitcnt lgkmcnt(2)
	v_mfma_f32_16x16x32_bf16 v[128:131], v[136:139], v[144:147], v[128:131]
	ds_read2_b64 v[144:147], v150 offset0:8 offset1:12
	v_add_u32_e32 v68, 0xffffff60, v151
	v_ashrrev_i32_e32 v69, 31, v68
	s_waitcnt lgkmcnt(2)
	v_mfma_f32_16x16x32_bf16 v[132:135], v[136:139], v[140:143], v[132:135]
	ds_read2_b64 v[140:143], v127 offset0:16 offset1:20
	v_lshlrev_b64 v[68:69], 12, v[68:69]
	v_lshl_add_u64 v[68:69], v[94:95], 0, v[68:69]
	s_waitcnt lgkmcnt(1)
	v_mfma_f32_16x16x32_bf16 v[62:65], v[136:139], v[144:147], v[62:65]
	ds_read2_b64 v[144:147], v148 offset0:16 offset1:20
	v_cvt_pk_bf16_f32 v136, v38, v39
	v_cvt_pk_bf16_f32 v137, v40, v41
	v_cvt_pk_bf16_f32 v138, v42, v43
	v_cvt_pk_bf16_f32 v139, v44, v45
	global_store_dwordx2 v[68:69], v[66:67], off
	s_waitcnt lgkmcnt(1)
	v_mfma_f32_16x16x32_bf16 v[58:61], v[136:139], v[140:143], v[58:61]
	ds_read2_b64 v[140:143], v150 offset0:16 offset1:20
	ds_read2_b64 v[66:69], v127 offset0:24 offset1:28
	s_add_i32 s35, s19, s97
	v_mfma_f32_16x16x32_bf16 v[132:135], v[136:139], v[98:101], v[132:135]
	ds_read2_b64 v[98:101], v148 offset0:24 offset1:28
	s_add_i32 s18, s18, 64
	s_waitcnt lgkmcnt(3)
	v_mfma_f32_16x16x32_bf16 v[128:131], v[136:139], v[144:147], v[128:131]
	v_add_u32_e32 v144, 0xffffff70, v151
	v_ashrrev_i32_e32 v145, 31, v144
	v_lshlrev_b64 v[144:145], 12, v[144:145]
	s_waitcnt lgkmcnt(2)
	v_mfma_f32_16x16x32_bf16 v[62:65], v[136:139], v[140:143], v[62:65]
	v_cvt_pk_bf16_f32 v136, v46, v47
	v_cvt_pk_bf16_f32 v137, v48, v49
	v_cvt_pk_bf16_f32 v138, v54, v55
	v_cvt_pk_bf16_f32 v139, v56, v57
	s_waitcnt lgkmcnt(1)
	v_mfma_f32_16x16x32_bf16 v[140:143], v[136:139], v[66:69], v[58:61]
	ds_read2_b64 v[66:69], v149 offset0:24 offset1:28
	s_waitcnt lgkmcnt(1)
	v_mfma_f32_16x16x32_bf16 v[58:61], v[136:139], v[98:101], v[128:131]
	v_lshl_add_u32 v98, v219, 2, s35
	v_add_u32_e32 v127, 0xd400, v98
	ds_read2_b32 v[98:99], v127 offset1:16
	v_lshl_add_u64 v[100:101], v[94:95], 0, v[144:145]
	ds_read2_b64 v[128:131], v150 offset0:24 offset1:28
	global_store_dwordx2 v[100:101], v[96:97], off
	v_mov_b32_e32 v97, s35
	v_lshl_add_u32 v100, v80, 2, s35
	s_mul_i32 s35, s93, 0x2400
	s_add_i32 s35, s19, s35
	v_lshlrev_b32_e32 v101, 1, v80
	v_add3_u32 v161, s35, v105, v101
	s_waitcnt lgkmcnt(2)
	v_mfma_f32_16x16x32_bf16 v[66:69], v[136:139], v[66:69], v[132:135]
	s_waitcnt lgkmcnt(1)
	v_mul_f32_e32 v96, 0x3fb8aa3b, v98
	ds_read_b32 v98, v97 offset:54524
	v_exp_f32_e32 v96, v96
	ds_read_b128 v[132:135], v161 offset:35840
	s_waitcnt lgkmcnt(2)
	v_mfma_f32_16x16x32_bf16 v[62:65], v[136:139], v[128:131], v[62:65]
	ds_read_b128 v[128:131], v100 offset:54784
	v_add3_u32 v186, s19, v101, v123
	v_pk_mul_f32 v[152:153], v[142:143], v[96:97] op_sel_hi:[1,0]
	s_waitcnt lgkmcnt(1)
	v_lshlrev_b32_e32 v144, 16, v132
	v_and_b32_e32 v132, 0xffff0000, v132
	v_pk_mul_f32 v[96:97], v[140:141], v[96:97] op_sel_hi:[1,0]
	ds_read_b128 v[136:139], v100 offset:54800
	ds_read_b128 v[140:143], v100 offset:54928
	s_waitcnt lgkmcnt(2)
	v_mul_f32_e32 v128, v128, v144
	v_mul_f32_e32 v129, v129, v132
	ds_read_b128 v[144:147], v100 offset:54912
	ds_read_b128 v[148:151], v186 offset:17408
	v_cvt_pk_bf16_f32 v128, v128, v129
	v_lshlrev_b32_e32 v129, 16, v133
	v_mul_f32_e32 v129, v130, v129
	v_and_b32_e32 v130, 0xffff0000, v133
	v_mul_f32_e32 v98, 0x3fb8aa3b, v98
	v_mul_f32_e32 v130, v131, v130
	v_exp_f32_e32 v98, v98
	v_cvt_pk_bf16_f32 v129, v129, v130
	v_lshlrev_b32_e32 v130, 16, v134
	s_waitcnt lgkmcnt(3)
	v_mul_f32_e32 v100, v136, v130
	v_and_b32_e32 v130, 0xffff0000, v134
	v_mul_f32_e32 v130, v137, v130
	v_cvt_pk_bf16_f32 v130, v100, v130
	v_lshlrev_b32_e32 v100, 16, v135
	v_and_b32_e32 v101, 0xffff0000, v135
	ds_read_b128 v[132:135], v186 offset:19712
	ds_read_b128 v[166:169], v186 offset:19776
	v_pk_mul_f32 v[52:53], v[98:99], v[52:53] op_sel_hi:[0,1]
	v_pk_mul_f32 v[50:51], v[98:99], v[50:51] op_sel_hi:[0,1]
	v_mul_f32_e32 v100, v138, v100
	v_mul_f32_e32 v101, v139, v101
	v_cvt_pk_bf16_f32 v131, v100, v101
	v_pk_mul_f32 v[28:29], v[98:99], v[28:29] op_sel_hi:[0,1]
	s_waitcnt lgkmcnt(2)
	v_mfma_f32_16x16x32_bf16 v[50:53], v[148:151], v[128:131], v[50:53]
	ds_read_b128 v[148:151], v186 offset:22016
	ds_read_b128 v[170:173], v186 offset:22080
	v_pk_mul_f32 v[26:27], v[98:99], v[26:27] op_sel_hi:[0,1]
	v_pk_mul_f32 v[32:33], v[98:99], v[32:33] op_sel_hi:[0,1]
	v_pk_mul_f32 v[30:31], v[98:99], v[30:31] op_sel_hi:[0,1]
	s_waitcnt lgkmcnt(3)
	v_mfma_f32_16x16x32_bf16 v[26:29], v[132:135], v[128:131], v[26:29]
	ds_read_b128 v[132:135], v186 offset:24320
	ds_read_b128 v[174:177], v186 offset:24384
	v_pk_mul_f32 v[36:37], v[98:99], v[36:37] op_sel_hi:[0,1]
	s_waitcnt lgkmcnt(3)
	v_mfma_f32_16x16x32_bf16 v[30:33], v[148:151], v[128:131], v[30:33]
	ds_read_b128 v[148:151], v186 offset:26624
	ds_read_b128 v[178:181], v186 offset:26688
	v_pk_mul_f32 v[34:35], v[98:99], v[34:35] op_sel_hi:[0,1]
	v_pk_mul_f32 v[40:41], v[98:99], v[40:41] op_sel_hi:[0,1]
	v_pk_mul_f32 v[38:39], v[98:99], v[38:39] op_sel_hi:[0,1]
	s_waitcnt lgkmcnt(3)
	v_mfma_f32_16x16x32_bf16 v[34:37], v[132:135], v[128:131], v[34:37]
	ds_read_b128 v[132:135], v186 offset:28928
	ds_read_b128 v[182:185], v186 offset:28992
	v_pk_mul_f32 v[44:45], v[98:99], v[44:45] op_sel_hi:[0,1]
	s_waitcnt lgkmcnt(3)
	v_mfma_f32_16x16x32_bf16 v[38:41], v[148:151], v[128:131], v[38:41]
	ds_read_b128 v[148:151], v186 offset:31232
	v_pk_mul_f32 v[42:43], v[98:99], v[42:43] op_sel_hi:[0,1]
	v_pk_mul_f32 v[48:49], v[98:99], v[48:49] op_sel_hi:[0,1]
	v_pk_mul_f32 v[46:47], v[98:99], v[46:47] op_sel_hi:[0,1]
	s_waitcnt lgkmcnt(2)
	v_mfma_f32_16x16x32_bf16 v[42:45], v[132:135], v[128:131], v[42:45]
	ds_read_b128 v[132:135], v186 offset:33536
	v_cvt_pk_bf16_f32 v100, v96, v97
	v_pk_mul_f32 v[56:57], v[98:99], v[56:57] op_sel_hi:[0,1]
	s_waitcnt lgkmcnt(1)
	v_mfma_f32_16x16x32_bf16 v[46:49], v[148:151], v[128:131], v[46:49]
	ds_read_b128 v[148:151], v161 offset:35904
	v_pk_mul_f32 v[54:55], v[98:99], v[54:55] op_sel_hi:[0,1]
	ds_read_b128 v[136:139], v186 offset:33600
	ds_read_b128 v[162:165], v186 offset:17472
	s_waitcnt lgkmcnt(3)
	v_mfma_f32_16x16x32_bf16 v[54:57], v[132:135], v[128:131], v[54:57]
	s_waitcnt lgkmcnt(2)
	v_lshlrev_b32_e32 v96, 16, v148
	v_mul_f32_e32 v96, v144, v96
	v_and_b32_e32 v97, 0xffff0000, v148
	v_mul_f32_e32 v97, v145, v97
	v_cvt_pk_bf16_f32 v128, v96, v97
	v_lshlrev_b32_e32 v96, 16, v149
	v_mul_f32_e32 v96, v146, v96
	v_and_b32_e32 v97, 0xffff0000, v149
	v_mul_f32_e32 v97, v147, v97
	v_cvt_pk_bf16_f32 v129, v96, v97
	v_lshlrev_b32_e32 v96, 16, v150
	v_mul_f32_e32 v96, v140, v96
	v_and_b32_e32 v97, 0xffff0000, v150
	v_mul_f32_e32 v97, v141, v97
	v_cvt_pk_bf16_f32 v130, v96, v97
	v_lshlrev_b32_e32 v96, 16, v151
	v_mul_f32_e32 v96, v142, v96
	v_and_b32_e32 v97, 0xffff0000, v151
	v_mul_f32_e32 v97, v143, v97
	v_cvt_pk_bf16_f32 v131, v96, v97
	v_mul_f32_e32 v96, 0x3fb8aa3b, v99
	v_exp_f32_e32 v96, v96
	ds_read2_b32 v[132:133], v127 offset0:32 offset1:48
	s_waitcnt lgkmcnt(1)
	v_mfma_f32_16x16x32_bf16 v[50:53], v[162:165], v[128:131], v[50:53]
	s_cmp_eq_u32 s48, s34
	v_pk_mul_f32 v[60:61], v[60:61], v[96:97] op_sel_hi:[1,0]
	v_pk_mul_f32 v[58:59], v[58:59], v[96:97] op_sel_hi:[1,0]
	v_cvt_pk_bf16_f32 v99, v60, v61
	s_waitcnt lgkmcnt(0)
	v_mul_f32_e32 v96, 0x3fb8aa3b, v132
	v_cvt_pk_bf16_f32 v98, v58, v59
	ds_read_b128 v[58:61], v186 offset:31296
	v_exp_f32_e32 v96, v96
	v_mfma_f32_16x16x32_bf16 v[26:29], v[166:169], v[128:131], v[26:29]
	v_cvt_pk_bf16_f32 v101, v152, v153
	s_waitcnt lgkmcnt(0)
	v_pk_mul_f32 v[68:69], v[68:69], v[96:97] op_sel_hi:[1,0]
	v_pk_mul_f32 v[66:67], v[66:67], v[96:97] op_sel_hi:[1,0]
	v_mul_f32_e32 v96, 0x3fb8aa3b, v133
	v_mfma_f32_16x16x32_bf16 v[30:33], v[170:173], v[128:131], v[30:33]
	v_exp_f32_e32 v96, v96
	v_cvt_pk_bf16_f32 v66, v66, v67
	v_cvt_pk_bf16_f32 v67, v68, v69
	v_mfma_f32_16x16x32_bf16 v[34:37], v[174:177], v[128:131], v[34:37]
	v_mul_f32_e64 v64, v64, v96
	v_mul_f32_e64 v65, v65, v96
	s_barrier
	v_mfma_f32_16x16x32_bf16 v[38:41], v[178:181], v[128:131], v[38:41]
	v_mfma_f32_16x16x32_bf16 v[42:45], v[182:185], v[128:131], v[42:45]
	v_mfma_f32_16x16x32_bf16 v[46:49], v[58:61], v[128:131], v[46:49]
	v_mul_f32_e64 v58, v62, v96
	v_mul_f32_e64 v59, v63, v96
	v_cvt_pk_bf16_f32 v97, v64, v65
	v_mfma_f32_16x16x32_bf16 v[54:57], v[136:139], v[128:131], v[54:57]
	v_cvt_pk_bf16_f32 v96, v58, v59
	s_cbranch_scc1 .LBB0_113
	s_mov_b32 s35, s34
	s_add_i32 s34, s35, 1
	s_cmp_ge_u32 s34, s48
	s_cbranch_scc0 .LBB0_106
	s_branch .LBB0_108
